# grid barrier 5 split-phase for the final-attention workgroups: they arrive, start staging their first item and wait for the release just before the loads that need phase-4 data
# speedup vs baseline: 1.0458x; 1.0092x over previous
.LBB0_634:
	s_or_b64 exec, exec, s[6:7]
	v_cvt_f32_u32_e32 v6, v4
	s_waitcnt vmcnt(0)
	v_readfirstlane_b32 s4, v5
	v_sub_u32_e32 v5, 0, v4
	v_rcp_iflag_f32_e32 v6, v6
	v_add_u32_e32 v7, s4, v3
	v_mul_f32_e32 v6, 0x4f7ffffe, v6
	v_cvt_u32_f32_e32 v6, v6
	v_mul_lo_u32 v3, v5, v6
	v_mul_hi_u32 v3, v6, v3
	v_add_u32_e32 v3, v6, v3
	v_mul_hi_u32 v3, v7, v3
	v_mul_lo_u32 v5, v3, v4
	v_sub_u32_e32 v5, v7, v5
	v_add_u32_e32 v6, 1, v3
	v_cmp_ge_u32_e32 vcc, v5, v4
	s_nop 1
	v_cndmask_b32_e32 v3, v3, v6, vcc
	v_sub_u32_e32 v6, v5, v4
	v_cndmask_b32_e32 v5, v5, v6, vcc
	v_add_u32_e32 v6, 1, v3
	v_cmp_ge_u32_e32 vcc, v5, v4
	v_add_u32_e32 v5, 1, v7
	s_nop 0
	v_cndmask_b32_e32 v3, v3, v6, vcc
	v_mul_lo_u32 v6, v4, v3
	v_add_u32_e32 v4, v6, v4
	v_cmp_ne_u32_e32 vcc, v5, v4
	s_and_saveexec_b64 s[4:5], vcc
	s_xor_b64 s[4:5], exec, s[4:5]
	s_cbranch_execz .LBB0_793
	s_waitcnt lgkmcnt(0)
	v_mov_b32_e32 v2, 0x7000
	buffer_inv sc1
	s_cmpk_gt_u32 s64, 0x7f
	s_cbranch_scc1 .Lsplit5_nl
	global_load_dword v2, v2, s[82:83] offset:1280 sc1
	s_add_u32 s10, s82, 0x7500
	s_addc_u32 s11, s83, 0
	s_waitcnt vmcnt(0)
	v_cmp_eq_u32_e32 vcc, v2, v3
	s_and_saveexec_b64 s[6:7], vcc
	s_cbranch_execz .LBB0_792
	s_add_u32 s8, s82, 0x4200
	s_addc_u32 s9, s83, 0
	s_mov_b32 s22, 1
	s_mov_b64 s[12:13], 0
	v_mov_b32_e32 v2, 0
	s_branch .LBB0_638

.Lsplit5_nl:
.LBB0_793:
	s_andn2_saveexec_b64 s[4:5], s[4:5]
	s_cbranch_execz .LBB0_829
	s_mov_b64 s[4:5], exec
	buffer_wbl2 sc1
	buffer_inv sc1
	s_waitcnt lgkmcnt(0)
	s_waitcnt vmcnt(0)
	v_mbcnt_lo_u32_b32 v3, s4, 0
	v_mbcnt_hi_u32_b32 v3, s5, v3
	v_cmp_eq_u32_e32 vcc, 0, v3
	s_and_saveexec_b64 s[6:7], vcc
	s_cbranch_execz .LBB0_796
	s_bcnt1_i32_b64 s4, s[4:5]
	v_mov_b32_e32 v4, 0x7000
	v_mov_b32_e32 v5, s4
	global_atomic_add v4, v4, v5, s[82:83] offset:1024 sc0
.LBB0_796:
	s_or_b64 exec, exec, s[6:7]
	v_cvt_f32_u32_e32 v5, v2
	s_waitcnt vmcnt(0)
	v_readfirstlane_b32 s4, v4
	s_add_u32 s6, s82, 0x7500
	s_addc_u32 s7, s83, 0
	v_rcp_iflag_f32_e32 v5, v5
	v_add_u32_e32 v3, s4, v3
	v_add_u32_e32 v6, 1, v3
	s_mov_b64 s[8:9], -1
	v_mul_f32_e32 v4, 0x4f7ffffe, v5
	v_cvt_u32_f32_e32 v4, v4
	v_sub_u32_e32 v5, 0, v2
	v_mul_lo_u32 v5, v5, v4
	v_mul_hi_u32 v5, v4, v5
	v_add_u32_e32 v4, v4, v5
	v_mul_hi_u32 v4, v3, v4
	v_mul_lo_u32 v5, v4, v2
	v_sub_u32_e32 v3, v3, v5
	v_add_u32_e32 v7, 1, v4
	v_cmp_ge_u32_e32 vcc, v3, v2
	v_sub_u32_e32 v5, v3, v2
	s_nop 0
	v_cndmask_b32_e32 v4, v4, v7, vcc
	v_cndmask_b32_e32 v3, v3, v5, vcc
	v_add_u32_e32 v5, 1, v4
	v_cmp_ge_u32_e32 vcc, v3, v2
	s_nop 1
	v_cndmask_b32_e32 v4, v4, v5, vcc
	v_mul_lo_u32 v3, v2, v4
	v_add_u32_e32 v2, v3, v2
	v_cmp_ne_u32_e32 vcc, v6, v2
	v_mov_b64_e32 v[2:3], s[6:7]
	s_and_saveexec_b64 s[4:5], vcc
	s_cbranch_execz .LBB0_824
	s_mov_b64 s[12:13], 0
	s_cmpk_gt_u32 s64, 0x7f
	s_cbranch_scc1 .Lsplit5_ld
	v_mov_b32_e32 v2, 0
	global_load_dword v3, v2, s[6:7] sc1
	s_mov_b64 s[12:13], 0
	s_waitcnt vmcnt(0)
	v_cmp_eq_u32_e32 vcc, v3, v4
	s_and_saveexec_b64 s[10:11], vcc
	s_cbranch_execz .LBB0_823
	s_add_u32 s8, s82, 0x4200
	s_addc_u32 s9, s83, 0
	s_mov_b32 s22, 1
	s_branch .LBB0_800

.Lsplit5_ld:
	v_mov_b64_e32 v[2:3], s[8:9]
	s_orn2_b64 s[8:9], s[12:13], exec

.LBB0_833:
	v_max_i32_e32 v2, 0, v6
	v_lshlrev_b64 v[8:9], 7, v[2:3]
	s_mov_b32 m0, s85
	v_lshl_add_u64 v[8:9], v[4:5], 0, v[8:9]
	global_load_lds_dwordx4 v[8:9], off
	s_add_i32 s7, s7, 1
	s_addk_i32 s85, 0x2000
	s_cmp_gt_u32 s7, 10
	v_add_u32_e32 v6, 32, v6
	s_cbranch_scc0 .LBB0_833
	s_lshl_b64 s[76:77], s[76:77], 1
	s_add_u32 s76, s93, s76
	s_addc_u32 s77, s94, s77
	s_add_i32 s7, s8, s88
	v_or_b32_e32 v4, s7, v197
	v_ashrrev_i32_e32 v5, 31, v4
	v_lshlrev_b64 v[4:5], 7, v[4:5]
	v_lshl_add_u64 v[4:5], s[76:77], 0, v[4:5]
	v_or_b32_e32 v192, s7, v196
	s_and_b32 s76, s84, 0x3fffffc0
	v_lshl_add_u64 v[4:5], v[4:5], 0, v[190:191]
	s_lshl_b32 s85, s74, 4
	s_lshl_b32 s76, s76, 1
	s_mov_b32 s77, s75
	v_lshl_or_b32 v2, s74, 2, v198
	v_ashrrev_i32_e32 v8, 2, v192
	global_load_dwordx4 v[94:97], v[4:5], off
	global_load_dwordx4 v[90:93], v[4:5], off offset:32
	global_load_dwordx4 v[86:89], v[4:5], off offset:64
	global_load_dwordx4 v[82:85], v[4:5], off offset:96
	s_cmp_lg_u32 s6, 0
	s_cbranch_scc1 .Lsplit5_go
	s_mov_b64 s[98:99], exec
	v_readlane_b32 s100, v254, 6
	v_readlane_b32 s101, v254, 7
	s_and_b64 s[100:101], s[98:99], s[100:101]
	s_mov_b64 exec, s[100:101]
	s_cbranch_execz .Lsplit5_join
	v_mov_b32_e32 v240, 0x7000
	s_mov_b32 s100, 0
.Lsplit5_spin:
	global_load_dword v241, v240, s[82:83] offset:1280 sc1
	s_waitcnt vmcnt(0)
	v_cmp_gt_u32_e32 vcc, 5, v241
	s_cbranch_vccz .Lsplit5_join
	s_sleep 1
	s_add_i32 s100, s100, 1
	s_and_b32 s101, s100, 0xff
	s_cmp_lg_u32 s101, 0
	s_cbranch_scc1 .Lsplit5_spin
	v_mov_b32_e32 v242, 0x4000
	global_load_dword v241, v242, s[82:83] offset:512 sc1
	s_waitcnt vmcnt(0)
	v_cmp_ne_u32_e32 vcc, 0, v241
	s_cbranch_vccnz .Lsplit5_join
	s_cmp_lt_u32 s100, 0x40001
	s_cbranch_scc1 .Lsplit5_spin
	v_mov_b32_e32 v241, 1
	global_atomic_add v242, v241, s[82:83] offset:512
	s_waitcnt vmcnt(0)
.Lsplit5_join:
	s_mov_b64 exec, s[98:99]
	s_barrier
.Lsplit5_go:
	v_lshl_add_u64 v[4:5], v[184:185], 0, s[76:77]
	v_lshlrev_b64 v[6:7], 12, v[2:3]
	v_ashrrev_i32_e32 v9, 31, v8
	v_or_b32_e32 v2, s85, v196
	s_ashr_i32 s76, s7, 4
	v_lshl_add_u64 v[8:9], v[6:7], 0, v[8:9]
	v_lshlrev_b64 v[10:11], 10, v[2:3]
	s_ashr_i32 s77, s76, 31
	v_lshl_add_u64 v[12:13], v[10:11], 0, s[76:77]
	v_lshlrev_b64 v[14:15], 7, v[8:9]
	v_lshl_add_u64 v[14:15], v[180:181], 0, v[14:15]
	v_lshlrev_b64 v[16:17], 7, v[12:13]
	v_ashrrev_i32_e32 v193, 31, v192
	v_lshl_add_u64 v[16:17], v[182:183], 0, v[16:17]
	global_load_dwordx4 v[142:145], v[14:15], off
	global_load_dwordx4 v[138:141], v[16:17], off
	v_lshlrev_b64 v[14:15], 10, v[192:193]
	v_lshl_add_u64 v[12:13], v[12:13], 2, s[0:1]
	v_lshl_add_u64 v[14:15], v[4:5], 0, v[14:15]
	v_lshl_add_u64 v[8:9], v[8:9], 2, s[0:1]
	v_add_co_u32_e32 v12, vcc, s4, v12
	s_cmp_ge_i32 s33, s9
	s_nop 0
	v_addc_co_u32_e32 v13, vcc, 0, v13, vcc
	global_load_dwordx4 v[134:137], v[14:15], off
	global_load_dword v230, v[8:9], off
	global_load_dword v231, v[12:13], off
	v_or_b32_e32 v8, 8, v192
	v_ashrrev_i32_e32 v12, 2, v8
	v_and_or_b32 v2, v8, 15, s85
	v_ashrrev_i32_e32 v13, 31, v12
	v_lshlrev_b64 v[14:15], 10, v[2:3]
	v_lshl_add_u64 v[12:13], v[6:7], 0, v[12:13]
	v_lshl_add_u64 v[14:15], v[14:15], 0, s[76:77]
	v_ashrrev_i32_e32 v9, 31, v8
	v_lshlrev_b64 v[16:17], 7, v[12:13]
	v_lshlrev_b64 v[18:19], 7, v[14:15]
	v_lshlrev_b64 v[8:9], 10, v[8:9]
	v_lshl_add_u64 v[14:15], v[14:15], 2, s[0:1]
	v_lshl_add_u64 v[16:17], v[180:181], 0, v[16:17]
	v_lshl_add_u64 v[8:9], v[4:5], 0, v[8:9]
	v_add_co_u32_e32 v14, vcc, s4, v14
	v_lshl_add_u64 v[18:19], v[182:183], 0, v[18:19]
	global_load_dwordx4 v[130:133], v[16:17], off
	global_load_dwordx4 v[126:129], v[18:19], off
	v_lshl_add_u64 v[12:13], v[12:13], 2, s[0:1]
	v_addc_co_u32_e32 v15, vcc, 0, v15, vcc
	global_load_dwordx4 v[122:125], v[8:9], off
	global_load_dword v228, v[12:13], off
	global_load_dword v229, v[14:15], off
	v_or_b32_e32 v8, 16, v192
	v_ashrrev_i32_e32 v12, 2, v8
	v_ashrrev_i32_e32 v14, 4, v8
	v_ashrrev_i32_e32 v13, 31, v12
	v_ashrrev_i32_e32 v15, 31, v14
	v_lshl_add_u64 v[12:13], v[6:7], 0, v[12:13]
	v_lshl_add_u64 v[10:11], v[10:11], 0, v[14:15]
	v_ashrrev_i32_e32 v9, 31, v8
	v_lshlrev_b64 v[14:15], 7, v[12:13]
	v_lshlrev_b64 v[16:17], 7, v[10:11]
	v_lshlrev_b64 v[8:9], 10, v[8:9]
	v_lshl_add_u64 v[10:11], v[10:11], 2, s[0:1]
	v_lshl_add_u64 v[14:15], v[180:181], 0, v[14:15]
	v_lshl_add_u64 v[8:9], v[4:5], 0, v[8:9]
	v_add_co_u32_e32 v10, vcc, s4, v10
	v_lshl_add_u64 v[16:17], v[182:183], 0, v[16:17]
	global_load_dwordx4 v[118:121], v[14:15], off
	global_load_dwordx4 v[114:117], v[16:17], off
	v_lshl_add_u64 v[12:13], v[12:13], 2, s[0:1]
	v_addc_co_u32_e32 v11, vcc, 0, v11, vcc
	global_load_dwordx4 v[110:113], v[8:9], off
	global_load_dword v226, v[12:13], off
	global_load_dword v227, v[10:11], off
	v_or_b32_e32 v8, 24, v192
	v_ashrrev_i32_e32 v10, 2, v8
	v_ashrrev_i32_e32 v11, 31, v10
	v_and_or_b32 v2, v8, 15, s85
	v_ashrrev_i32_e32 v12, 4, v8
	v_lshl_add_u64 v[6:7], v[6:7], 0, v[10:11]
	v_lshlrev_b64 v[10:11], 10, v[2:3]
	v_ashrrev_i32_e32 v13, 31, v12
	v_ashrrev_i32_e32 v9, 31, v8
	v_lshl_add_u64 v[10:11], v[10:11], 0, v[12:13]
	v_lshlrev_b64 v[8:9], 10, v[8:9]
	v_lshlrev_b64 v[12:13], 7, v[6:7]
	v_lshl_add_u64 v[4:5], v[4:5], 0, v[8:9]
	v_lshl_add_u64 v[8:9], v[10:11], 2, s[0:1]
	v_lshl_add_u64 v[12:13], v[180:181], 0, v[12:13]
	v_lshlrev_b64 v[14:15], 7, v[10:11]
	v_add_co_u32_e32 v8, vcc, 0x80000, v8
	v_lshl_add_u64 v[14:15], v[182:183], 0, v[14:15]
	global_load_dwordx4 v[106:109], v[12:13], off
	global_load_dwordx4 v[102:105], v[14:15], off
	v_lshl_add_u64 v[6:7], v[6:7], 2, s[0:1]
	v_addc_co_u32_e32 v9, vcc, 0, v9, vcc
	global_load_dwordx4 v[98:101], v[4:5], off
	global_load_dword v224, v[6:7], off
	global_load_dword v225, v[8:9], off
	s_waitcnt vmcnt(0)
	s_cselect_b64 s[76:77], -1, 0
	s_and_b64 vcc, exec, s[76:77]
	v_add_u32_e32 v34, v209, v202
	v_add_u32_e32 v35, v209, v201
	v_add_u32_e32 v36, v209, v200
	s_waitcnt vmcnt(0) lgkmcnt(0)
	s_barrier
	s_cbranch_vccz .LBB0_836
	ds_read_b128 v[4:7], v221
	ds_read_b128 v[8:11], v34
	ds_read_b128 v[12:15], v35
	ds_read_b128 v[16:19], v36
	s_waitcnt lgkmcnt(0)
	v_mfma_f32_32x32x16_bf16 v[18:33], v[16:19], v[94:97], 0
	v_add_u32_e32 v2, s95, v204
	ds_read_b64_tr_b16 v[146:147], v2 offset:4096
	ds_read_b64_tr_b16 v[148:149], v2 offset:5120
	ds_read_b64_tr_b16 v[150:151], v2 offset:6144
	ds_read_b64_tr_b16 v[152:153], v2 offset:7168
	v_add_u32_e32 v2, s95, v205
	ds_read_b64_tr_b16 v[158:159], v2 offset:4096
	ds_read_b64_tr_b16 v[160:161], v2 offset:5120
	ds_read_b64_tr_b16 v[154:155], v2 offset:6144
	ds_read_b64_tr_b16 v[156:157], v2 offset:7168
	v_mfma_f32_32x32x16_bf16 v[18:33], v[12:15], v[90:93], v[18:33]
	v_mfma_f32_32x32x16_bf16 v[18:33], v[8:11], v[86:89], v[18:33]
	v_mfma_f32_32x32x16_bf16 v[18:33], v[4:7], v[82:85], v[18:33]
	s_branch .LBB0_837
